# plus FFN-up SwiGLU epilogue rewritten by hand with packed f32 ops and 8-wide ILP (same arithmetic, bit-identical), global stores
# baseline (speedup 1.0000x reference)
.LBB0_564:
	v_lshl_add_u32 v216, s20, 8, v144
	v_lshl_or_b32 v218, s57, 7, v162
	v_mov_b32_e32 v224, s26
	v_mov_b32_e32 v225, s27
	v_ashrrev_i32_e32 v219, 31, v218
	v_mov_b32_e32 v226, 0x358637bd
	v_lshlrev_b64 v[218:219], 1, v[218:219]
	v_mad_i64_i32 v[228:229], s[2:3], v216, s14, v[224:225]
	s_mov_b64 s[40:41], 0x16000
	s_mov_b64 s[6:7], 0xb0000
	v_ffbh_u32_e32 v208, v159
	v_ffbh_u32_e32 v209, v157
	v_ffbh_u32_e32 v210, v155
	v_ffbh_u32_e32 v211, v153
	v_ffbh_u32_e32 v212, v151
	v_ffbh_u32_e32 v213, v149
	v_ffbh_u32_e32 v214, v143
	v_ffbh_u32_e32 v215, v141
	v_min_u32_e32 v208, 32, v208
	v_min_u32_e32 v209, 32, v209
	v_min_u32_e32 v210, 32, v210
	v_min_u32_e32 v211, 32, v211
	v_min_u32_e32 v212, 32, v212
	v_min_u32_e32 v213, 32, v213
	v_min_u32_e32 v214, 32, v214
	v_min_u32_e32 v215, 32, v215
	v_lshlrev_b64 v[158:159], v208, v[158:159]
	v_lshlrev_b64 v[156:157], v209, v[156:157]
	v_lshlrev_b64 v[154:155], v210, v[154:155]
	v_lshlrev_b64 v[152:153], v211, v[152:153]
	v_lshlrev_b64 v[150:151], v212, v[150:151]
	v_lshlrev_b64 v[148:149], v213, v[148:149]
	v_lshlrev_b64 v[142:143], v214, v[142:143]
	v_lshlrev_b64 v[140:141], v215, v[140:141]
	v_min_u32_e32 v158, 1, v158
	v_min_u32_e32 v156, 1, v156
	v_min_u32_e32 v154, 1, v154
	v_min_u32_e32 v152, 1, v152
	v_min_u32_e32 v150, 1, v150
	v_min_u32_e32 v148, 1, v148
	v_min_u32_e32 v142, 1, v142
	v_min_u32_e32 v140, 1, v140
	v_or_b32_e32 v159, v159, v158
	v_or_b32_e32 v157, v157, v156
	v_or_b32_e32 v155, v155, v154
	v_or_b32_e32 v153, v153, v152
	v_or_b32_e32 v151, v151, v150
	v_or_b32_e32 v149, v149, v148
	v_or_b32_e32 v143, v143, v142
	v_or_b32_e32 v141, v141, v140
	v_cvt_f32_u32_e32 v159, v159
	v_cvt_f32_u32_e32 v157, v157
	v_cvt_f32_u32_e32 v155, v155
	v_cvt_f32_u32_e32 v153, v153
	v_cvt_f32_u32_e32 v151, v151
	v_cvt_f32_u32_e32 v149, v149
	v_cvt_f32_u32_e32 v143, v143
	v_cvt_f32_u32_e32 v141, v141
	v_sub_u32_e32 v208, 32, v208
	v_sub_u32_e32 v209, 32, v209
	v_sub_u32_e32 v210, 32, v210
	v_sub_u32_e32 v211, 32, v211
	v_sub_u32_e32 v212, 32, v212
	v_sub_u32_e32 v213, 32, v213
	v_sub_u32_e32 v214, 32, v214
	v_sub_u32_e32 v215, 32, v215
	v_ldexp_f32 v184, v159, v208
	v_ldexp_f32 v186, v157, v209
	v_ldexp_f32 v188, v155, v210
	v_ldexp_f32 v190, v153, v211
	v_ldexp_f32 v192, v151, v212
	v_ldexp_f32 v194, v149, v213
	v_ldexp_f32 v196, v143, v214
	v_ldexp_f32 v198, v141, v215
	v_mul_f32_e32 v184, 0x35800000, v184
	v_mul_f32_e32 v186, 0x35800000, v186
	v_mul_f32_e32 v188, 0x35800000, v188
	v_mul_f32_e32 v190, 0x35800000, v190
	v_mul_f32_e32 v192, 0x35800000, v192
	v_mul_f32_e32 v194, 0x35800000, v194
	v_mul_f32_e32 v196, 0x35800000, v196
	v_mul_f32_e32 v198, 0x35800000, v198
	s_mov_b32 s2, 0x3a800000
	v_fma_f32 v184, v184, s2, v226
	v_fma_f32 v186, v186, s2, v226
	v_fma_f32 v188, v188, s2, v226
	v_fma_f32 v190, v190, s2, v226
	v_fma_f32 v192, v192, s2, v226
	v_fma_f32 v194, v194, s2, v226
	v_fma_f32 v196, v196, s2, v226
	v_fma_f32 v198, v198, s2, v226
	v_rsq_f32_e32 v184, v184
	v_rsq_f32_e32 v186, v186
	v_rsq_f32_e32 v188, v188
	v_rsq_f32_e32 v190, v190
	v_rsq_f32_e32 v192, v192
	v_rsq_f32_e32 v194, v194
	v_rsq_f32_e32 v196, v196
	v_rsq_f32_e32 v198, v198
	v_lshl_add_u64 v[228:229], v[228:229], 0, v[218:219]
	v_lshl_add_u64 v[230:231], v[228:229], 0, s[40:41]
	v_lshl_add_u64 v[236:237], v[228:229], 0, s[6:7]
	v_lshl_add_u64 v[232:233], v[230:231], 0, s[40:41]
	v_lshl_add_u64 v[238:239], v[230:231], 0, s[6:7]
	v_lshl_add_u64 v[234:235], v[232:233], 0, s[40:41]
	v_lshl_add_u64 v[240:241], v[232:233], 0, s[6:7]
	v_lshl_add_u64 v[242:243], v[234:235], 0, s[6:7]
	s_mov_b32 s40, 0xbfb8aa3b
	s_mov_b32 s6, 1.0
	v_pk_mul_f32 v[126:127], v[184:185], v[126:127] op_sel_hi:[0,1]
	v_pk_mul_f32 v[128:129], v[184:185], v[128:129] op_sel_hi:[0,1]
	v_pk_mul_f32 v[122:123], v[184:185], v[122:123] op_sel_hi:[0,1]
	v_pk_mul_f32 v[124:125], v[184:185], v[124:125] op_sel_hi:[0,1]
	v_pk_mul_f32 v[118:119], v[184:185], v[118:119] op_sel_hi:[0,1]
	v_pk_mul_f32 v[120:121], v[184:185], v[120:121] op_sel_hi:[0,1]
	v_pk_mul_f32 v[114:115], v[184:185], v[114:115] op_sel_hi:[0,1]
	v_pk_mul_f32 v[116:117], v[184:185], v[116:117] op_sel_hi:[0,1]
	v_pk_mul_f32 v[200:201], v[126:127], s[40:41] op_sel_hi:[1,0]
	v_pk_mul_f32 v[202:203], v[128:129], s[40:41] op_sel_hi:[1,0]
	v_pk_mul_f32 v[204:205], v[122:123], s[40:41] op_sel_hi:[1,0]
	v_pk_mul_f32 v[206:207], v[124:125], s[40:41] op_sel_hi:[1,0]
	v_exp_f32_e32 v200, v200
	v_exp_f32_e32 v201, v201
	v_exp_f32_e32 v202, v202
	v_exp_f32_e32 v203, v203
	v_exp_f32_e32 v204, v204
	v_exp_f32_e32 v205, v205
	v_exp_f32_e32 v206, v206
	v_exp_f32_e32 v207, v207
	v_pk_add_f32 v[200:201], v[200:201], s[6:7] op_sel_hi:[1,0]
	v_pk_add_f32 v[202:203], v[202:203], s[6:7] op_sel_hi:[1,0]
	v_pk_add_f32 v[204:205], v[204:205], s[6:7] op_sel_hi:[1,0]
	v_pk_add_f32 v[206:207], v[206:207], s[6:7] op_sel_hi:[1,0]
	v_rcp_f32_e32 v200, v200
	v_rcp_f32_e32 v201, v201
	v_rcp_f32_e32 v202, v202
	v_rcp_f32_e32 v203, v203
	v_rcp_f32_e32 v204, v204
	v_rcp_f32_e32 v205, v205
	v_rcp_f32_e32 v206, v206
	v_rcp_f32_e32 v207, v207
	v_pk_mul_f32 v[126:127], v[126:127], v[200:201]
	v_pk_mul_f32 v[128:129], v[128:129], v[202:203]
	v_pk_mul_f32 v[122:123], v[122:123], v[204:205]
	v_pk_mul_f32 v[124:125], v[124:125], v[206:207]
	v_pk_mul_f32 v[126:127], v[126:127], v[118:119]
	v_pk_mul_f32 v[128:129], v[128:129], v[120:121]
	v_pk_mul_f32 v[122:123], v[122:123], v[114:115]
	v_pk_mul_f32 v[124:125], v[124:125], v[116:117]
	v_cvt_pk_bf16_f32 v126, v126, v127
	v_cvt_pk_bf16_f32 v127, v128, v129
	v_cvt_pk_bf16_f32 v128, v122, v123
	v_cvt_pk_bf16_f32 v129, v124, v125
	global_store_dwordx4 v[228:229], v[126:129], off
	v_pk_mul_f32 v[110:111], v[186:187], v[110:111] op_sel_hi:[0,1]
	v_pk_mul_f32 v[112:113], v[186:187], v[112:113] op_sel_hi:[0,1]
	v_pk_mul_f32 v[106:107], v[186:187], v[106:107] op_sel_hi:[0,1]
	v_pk_mul_f32 v[108:109], v[186:187], v[108:109] op_sel_hi:[0,1]
	v_pk_mul_f32 v[102:103], v[186:187], v[102:103] op_sel_hi:[0,1]
	v_pk_mul_f32 v[104:105], v[186:187], v[104:105] op_sel_hi:[0,1]
	v_pk_mul_f32 v[98:99], v[186:187], v[98:99] op_sel_hi:[0,1]
	v_pk_mul_f32 v[100:101], v[186:187], v[100:101] op_sel_hi:[0,1]
	v_pk_mul_f32 v[200:201], v[110:111], s[40:41] op_sel_hi:[1,0]
	v_pk_mul_f32 v[202:203], v[112:113], s[40:41] op_sel_hi:[1,0]
	v_pk_mul_f32 v[204:205], v[106:107], s[40:41] op_sel_hi:[1,0]
	v_pk_mul_f32 v[206:207], v[108:109], s[40:41] op_sel_hi:[1,0]
	v_exp_f32_e32 v200, v200
	v_exp_f32_e32 v201, v201
	v_exp_f32_e32 v202, v202
	v_exp_f32_e32 v203, v203
	v_exp_f32_e32 v204, v204
	v_exp_f32_e32 v205, v205
	v_exp_f32_e32 v206, v206
	v_exp_f32_e32 v207, v207
	v_pk_add_f32 v[200:201], v[200:201], s[6:7] op_sel_hi:[1,0]
	v_pk_add_f32 v[202:203], v[202:203], s[6:7] op_sel_hi:[1,0]
	v_pk_add_f32 v[204:205], v[204:205], s[6:7] op_sel_hi:[1,0]
	v_pk_add_f32 v[206:207], v[206:207], s[6:7] op_sel_hi:[1,0]
	v_rcp_f32_e32 v200, v200
	v_rcp_f32_e32 v201, v201
	v_rcp_f32_e32 v202, v202
	v_rcp_f32_e32 v203, v203
	v_rcp_f32_e32 v204, v204
	v_rcp_f32_e32 v205, v205
	v_rcp_f32_e32 v206, v206
	v_rcp_f32_e32 v207, v207
	v_pk_mul_f32 v[110:111], v[110:111], v[200:201]
	v_pk_mul_f32 v[112:113], v[112:113], v[202:203]
	v_pk_mul_f32 v[106:107], v[106:107], v[204:205]
	v_pk_mul_f32 v[108:109], v[108:109], v[206:207]
	v_pk_mul_f32 v[110:111], v[110:111], v[102:103]
	v_pk_mul_f32 v[112:113], v[112:113], v[104:105]
	v_pk_mul_f32 v[106:107], v[106:107], v[98:99]
	v_pk_mul_f32 v[108:109], v[108:109], v[100:101]
	v_cvt_pk_bf16_f32 v110, v110, v111
	v_cvt_pk_bf16_f32 v111, v112, v113
	v_cvt_pk_bf16_f32 v112, v106, v107
	v_cvt_pk_bf16_f32 v113, v108, v109
	global_store_dwordx4 v[230:231], v[110:113], off
	v_pk_mul_f32 v[94:95], v[188:189], v[94:95] op_sel_hi:[0,1]
	v_pk_mul_f32 v[96:97], v[188:189], v[96:97] op_sel_hi:[0,1]
	v_pk_mul_f32 v[90:91], v[188:189], v[90:91] op_sel_hi:[0,1]
	v_pk_mul_f32 v[92:93], v[188:189], v[92:93] op_sel_hi:[0,1]
	v_pk_mul_f32 v[86:87], v[188:189], v[86:87] op_sel_hi:[0,1]
	v_pk_mul_f32 v[88:89], v[188:189], v[88:89] op_sel_hi:[0,1]
	v_pk_mul_f32 v[82:83], v[188:189], v[82:83] op_sel_hi:[0,1]
	v_pk_mul_f32 v[84:85], v[188:189], v[84:85] op_sel_hi:[0,1]
	v_pk_mul_f32 v[200:201], v[94:95], s[40:41] op_sel_hi:[1,0]
	v_pk_mul_f32 v[202:203], v[96:97], s[40:41] op_sel_hi:[1,0]
	v_pk_mul_f32 v[204:205], v[90:91], s[40:41] op_sel_hi:[1,0]
	v_pk_mul_f32 v[206:207], v[92:93], s[40:41] op_sel_hi:[1,0]
	v_exp_f32_e32 v200, v200
	v_exp_f32_e32 v201, v201
	v_exp_f32_e32 v202, v202
	v_exp_f32_e32 v203, v203
	v_exp_f32_e32 v204, v204
	v_exp_f32_e32 v205, v205
	v_exp_f32_e32 v206, v206
	v_exp_f32_e32 v207, v207
	v_pk_add_f32 v[200:201], v[200:201], s[6:7] op_sel_hi:[1,0]
	v_pk_add_f32 v[202:203], v[202:203], s[6:7] op_sel_hi:[1,0]
	v_pk_add_f32 v[204:205], v[204:205], s[6:7] op_sel_hi:[1,0]
	v_pk_add_f32 v[206:207], v[206:207], s[6:7] op_sel_hi:[1,0]
	v_rcp_f32_e32 v200, v200
	v_rcp_f32_e32 v201, v201
	v_rcp_f32_e32 v202, v202
	v_rcp_f32_e32 v203, v203
	v_rcp_f32_e32 v204, v204
	v_rcp_f32_e32 v205, v205
	v_rcp_f32_e32 v206, v206
	v_rcp_f32_e32 v207, v207
	v_pk_mul_f32 v[94:95], v[94:95], v[200:201]
	v_pk_mul_f32 v[96:97], v[96:97], v[202:203]
	v_pk_mul_f32 v[90:91], v[90:91], v[204:205]
	v_pk_mul_f32 v[92:93], v[92:93], v[206:207]
	v_pk_mul_f32 v[94:95], v[94:95], v[86:87]
	v_pk_mul_f32 v[96:97], v[96:97], v[88:89]
	v_pk_mul_f32 v[90:91], v[90:91], v[82:83]
	v_pk_mul_f32 v[92:93], v[92:93], v[84:85]
	v_cvt_pk_bf16_f32 v94, v94, v95
	v_cvt_pk_bf16_f32 v95, v96, v97
	v_cvt_pk_bf16_f32 v96, v90, v91
	v_cvt_pk_bf16_f32 v97, v92, v93
	global_store_dwordx4 v[232:233], v[94:97], off
	v_pk_mul_f32 v[78:79], v[190:191], v[78:79] op_sel_hi:[0,1]
	v_pk_mul_f32 v[80:81], v[190:191], v[80:81] op_sel_hi:[0,1]
	v_pk_mul_f32 v[74:75], v[190:191], v[74:75] op_sel_hi:[0,1]
	v_pk_mul_f32 v[76:77], v[190:191], v[76:77] op_sel_hi:[0,1]
	v_pk_mul_f32 v[70:71], v[190:191], v[70:71] op_sel_hi:[0,1]
	v_pk_mul_f32 v[72:73], v[190:191], v[72:73] op_sel_hi:[0,1]
	v_pk_mul_f32 v[66:67], v[190:191], v[66:67] op_sel_hi:[0,1]
	v_pk_mul_f32 v[68:69], v[190:191], v[68:69] op_sel_hi:[0,1]
	v_pk_mul_f32 v[200:201], v[78:79], s[40:41] op_sel_hi:[1,0]
	v_pk_mul_f32 v[202:203], v[80:81], s[40:41] op_sel_hi:[1,0]
	v_pk_mul_f32 v[204:205], v[74:75], s[40:41] op_sel_hi:[1,0]
	v_pk_mul_f32 v[206:207], v[76:77], s[40:41] op_sel_hi:[1,0]
	v_exp_f32_e32 v200, v200
	v_exp_f32_e32 v201, v201
	v_exp_f32_e32 v202, v202
	v_exp_f32_e32 v203, v203
	v_exp_f32_e32 v204, v204
	v_exp_f32_e32 v205, v205
	v_exp_f32_e32 v206, v206
	v_exp_f32_e32 v207, v207
	v_pk_add_f32 v[200:201], v[200:201], s[6:7] op_sel_hi:[1,0]
	v_pk_add_f32 v[202:203], v[202:203], s[6:7] op_sel_hi:[1,0]
	v_pk_add_f32 v[204:205], v[204:205], s[6:7] op_sel_hi:[1,0]
	v_pk_add_f32 v[206:207], v[206:207], s[6:7] op_sel_hi:[1,0]
	v_rcp_f32_e32 v200, v200
	v_rcp_f32_e32 v201, v201
	v_rcp_f32_e32 v202, v202
	v_rcp_f32_e32 v203, v203
	v_rcp_f32_e32 v204, v204
	v_rcp_f32_e32 v205, v205
	v_rcp_f32_e32 v206, v206
	v_rcp_f32_e32 v207, v207
	v_pk_mul_f32 v[78:79], v[78:79], v[200:201]
	v_pk_mul_f32 v[80:81], v[80:81], v[202:203]
	v_pk_mul_f32 v[74:75], v[74:75], v[204:205]
	v_pk_mul_f32 v[76:77], v[76:77], v[206:207]
	v_pk_mul_f32 v[78:79], v[78:79], v[70:71]
	v_pk_mul_f32 v[80:81], v[80:81], v[72:73]
	v_pk_mul_f32 v[74:75], v[74:75], v[66:67]
	v_pk_mul_f32 v[76:77], v[76:77], v[68:69]
	v_cvt_pk_bf16_f32 v78, v78, v79
	v_cvt_pk_bf16_f32 v79, v80, v81
	v_cvt_pk_bf16_f32 v80, v74, v75
	v_cvt_pk_bf16_f32 v81, v76, v77
	global_store_dwordx4 v[234:235], v[78:81], off
	v_pk_mul_f32 v[62:63], v[192:193], v[62:63] op_sel_hi:[0,1]
	v_pk_mul_f32 v[64:65], v[192:193], v[64:65] op_sel_hi:[0,1]
	v_pk_mul_f32 v[58:59], v[192:193], v[58:59] op_sel_hi:[0,1]
	v_pk_mul_f32 v[60:61], v[192:193], v[60:61] op_sel_hi:[0,1]
	v_pk_mul_f32 v[54:55], v[192:193], v[54:55] op_sel_hi:[0,1]
	v_pk_mul_f32 v[56:57], v[192:193], v[56:57] op_sel_hi:[0,1]
	v_pk_mul_f32 v[50:51], v[192:193], v[50:51] op_sel_hi:[0,1]
	v_pk_mul_f32 v[52:53], v[192:193], v[52:53] op_sel_hi:[0,1]
	v_pk_mul_f32 v[200:201], v[62:63], s[40:41] op_sel_hi:[1,0]
	v_pk_mul_f32 v[202:203], v[64:65], s[40:41] op_sel_hi:[1,0]
	v_pk_mul_f32 v[204:205], v[58:59], s[40:41] op_sel_hi:[1,0]
	v_pk_mul_f32 v[206:207], v[60:61], s[40:41] op_sel_hi:[1,0]
	v_exp_f32_e32 v200, v200
	v_exp_f32_e32 v201, v201
	v_exp_f32_e32 v202, v202
	v_exp_f32_e32 v203, v203
	v_exp_f32_e32 v204, v204
	v_exp_f32_e32 v205, v205
	v_exp_f32_e32 v206, v206
	v_exp_f32_e32 v207, v207
	v_pk_add_f32 v[200:201], v[200:201], s[6:7] op_sel_hi:[1,0]
	v_pk_add_f32 v[202:203], v[202:203], s[6:7] op_sel_hi:[1,0]
	v_pk_add_f32 v[204:205], v[204:205], s[6:7] op_sel_hi:[1,0]
	v_pk_add_f32 v[206:207], v[206:207], s[6:7] op_sel_hi:[1,0]
	v_rcp_f32_e32 v200, v200
	v_rcp_f32_e32 v201, v201
	v_rcp_f32_e32 v202, v202
	v_rcp_f32_e32 v203, v203
	v_rcp_f32_e32 v204, v204
	v_rcp_f32_e32 v205, v205
	v_rcp_f32_e32 v206, v206
	v_rcp_f32_e32 v207, v207
	v_pk_mul_f32 v[62:63], v[62:63], v[200:201]
	v_pk_mul_f32 v[64:65], v[64:65], v[202:203]
	v_pk_mul_f32 v[58:59], v[58:59], v[204:205]
	v_pk_mul_f32 v[60:61], v[60:61], v[206:207]
	v_pk_mul_f32 v[62:63], v[62:63], v[54:55]
	v_pk_mul_f32 v[64:65], v[64:65], v[56:57]
	v_pk_mul_f32 v[58:59], v[58:59], v[50:51]
	v_pk_mul_f32 v[60:61], v[60:61], v[52:53]
	v_cvt_pk_bf16_f32 v62, v62, v63
	v_cvt_pk_bf16_f32 v63, v64, v65
	v_cvt_pk_bf16_f32 v64, v58, v59
	v_cvt_pk_bf16_f32 v65, v60, v61
	global_store_dwordx4 v[236:237], v[62:65], off
	v_pk_mul_f32 v[46:47], v[194:195], v[46:47] op_sel_hi:[0,1]
	v_pk_mul_f32 v[48:49], v[194:195], v[48:49] op_sel_hi:[0,1]
	v_pk_mul_f32 v[42:43], v[194:195], v[42:43] op_sel_hi:[0,1]
	v_pk_mul_f32 v[44:45], v[194:195], v[44:45] op_sel_hi:[0,1]
	v_pk_mul_f32 v[38:39], v[194:195], v[38:39] op_sel_hi:[0,1]
	v_pk_mul_f32 v[40:41], v[194:195], v[40:41] op_sel_hi:[0,1]
	v_pk_mul_f32 v[34:35], v[194:195], v[34:35] op_sel_hi:[0,1]
	v_pk_mul_f32 v[36:37], v[194:195], v[36:37] op_sel_hi:[0,1]
	v_pk_mul_f32 v[200:201], v[46:47], s[40:41] op_sel_hi:[1,0]
	v_pk_mul_f32 v[202:203], v[48:49], s[40:41] op_sel_hi:[1,0]
	v_pk_mul_f32 v[204:205], v[42:43], s[40:41] op_sel_hi:[1,0]
	v_pk_mul_f32 v[206:207], v[44:45], s[40:41] op_sel_hi:[1,0]
	v_exp_f32_e32 v200, v200
	v_exp_f32_e32 v201, v201
	v_exp_f32_e32 v202, v202
	v_exp_f32_e32 v203, v203
	v_exp_f32_e32 v204, v204
	v_exp_f32_e32 v205, v205
	v_exp_f32_e32 v206, v206
	v_exp_f32_e32 v207, v207
	v_pk_add_f32 v[200:201], v[200:201], s[6:7] op_sel_hi:[1,0]
	v_pk_add_f32 v[202:203], v[202:203], s[6:7] op_sel_hi:[1,0]
	v_pk_add_f32 v[204:205], v[204:205], s[6:7] op_sel_hi:[1,0]
	v_pk_add_f32 v[206:207], v[206:207], s[6:7] op_sel_hi:[1,0]
	v_rcp_f32_e32 v200, v200
	v_rcp_f32_e32 v201, v201
	v_rcp_f32_e32 v202, v202
	v_rcp_f32_e32 v203, v203
	v_rcp_f32_e32 v204, v204
	v_rcp_f32_e32 v205, v205
	v_rcp_f32_e32 v206, v206
	v_rcp_f32_e32 v207, v207
	v_pk_mul_f32 v[46:47], v[46:47], v[200:201]
	v_pk_mul_f32 v[48:49], v[48:49], v[202:203]
	v_pk_mul_f32 v[42:43], v[42:43], v[204:205]
	v_pk_mul_f32 v[44:45], v[44:45], v[206:207]
	v_pk_mul_f32 v[46:47], v[46:47], v[38:39]
	v_pk_mul_f32 v[48:49], v[48:49], v[40:41]
	v_pk_mul_f32 v[42:43], v[42:43], v[34:35]
	v_pk_mul_f32 v[44:45], v[44:45], v[36:37]
	v_cvt_pk_bf16_f32 v46, v46, v47
	v_cvt_pk_bf16_f32 v47, v48, v49
	v_cvt_pk_bf16_f32 v48, v42, v43
	v_cvt_pk_bf16_f32 v49, v44, v45
	global_store_dwordx4 v[238:239], v[46:49], off
	v_pk_mul_f32 v[30:31], v[196:197], v[30:31] op_sel_hi:[0,1]
	v_pk_mul_f32 v[32:33], v[196:197], v[32:33] op_sel_hi:[0,1]
	v_pk_mul_f32 v[26:27], v[196:197], v[26:27] op_sel_hi:[0,1]
	v_pk_mul_f32 v[28:29], v[196:197], v[28:29] op_sel_hi:[0,1]
	v_pk_mul_f32 v[22:23], v[196:197], v[22:23] op_sel_hi:[0,1]
	v_pk_mul_f32 v[24:25], v[196:197], v[24:25] op_sel_hi:[0,1]
	v_pk_mul_f32 v[18:19], v[196:197], v[18:19] op_sel_hi:[0,1]
	v_pk_mul_f32 v[20:21], v[196:197], v[20:21] op_sel_hi:[0,1]
	v_pk_mul_f32 v[200:201], v[30:31], s[40:41] op_sel_hi:[1,0]
	v_pk_mul_f32 v[202:203], v[32:33], s[40:41] op_sel_hi:[1,0]
	v_pk_mul_f32 v[204:205], v[26:27], s[40:41] op_sel_hi:[1,0]
	v_pk_mul_f32 v[206:207], v[28:29], s[40:41] op_sel_hi:[1,0]
	v_exp_f32_e32 v200, v200
	v_exp_f32_e32 v201, v201
	v_exp_f32_e32 v202, v202
	v_exp_f32_e32 v203, v203
	v_exp_f32_e32 v204, v204
	v_exp_f32_e32 v205, v205
	v_exp_f32_e32 v206, v206
	v_exp_f32_e32 v207, v207
	v_pk_add_f32 v[200:201], v[200:201], s[6:7] op_sel_hi:[1,0]
	v_pk_add_f32 v[202:203], v[202:203], s[6:7] op_sel_hi:[1,0]
	v_pk_add_f32 v[204:205], v[204:205], s[6:7] op_sel_hi:[1,0]
	v_pk_add_f32 v[206:207], v[206:207], s[6:7] op_sel_hi:[1,0]
	v_rcp_f32_e32 v200, v200
	v_rcp_f32_e32 v201, v201
	v_rcp_f32_e32 v202, v202
	v_rcp_f32_e32 v203, v203
	v_rcp_f32_e32 v204, v204
	v_rcp_f32_e32 v205, v205
	v_rcp_f32_e32 v206, v206
	v_rcp_f32_e32 v207, v207
	v_pk_mul_f32 v[30:31], v[30:31], v[200:201]
	v_pk_mul_f32 v[32:33], v[32:33], v[202:203]
	v_pk_mul_f32 v[26:27], v[26:27], v[204:205]
	v_pk_mul_f32 v[28:29], v[28:29], v[206:207]
	v_pk_mul_f32 v[30:31], v[30:31], v[22:23]
	v_pk_mul_f32 v[32:33], v[32:33], v[24:25]
	v_pk_mul_f32 v[26:27], v[26:27], v[18:19]
	v_pk_mul_f32 v[28:29], v[28:29], v[20:21]
	v_cvt_pk_bf16_f32 v30, v30, v31
	v_cvt_pk_bf16_f32 v31, v32, v33
	v_cvt_pk_bf16_f32 v32, v26, v27
	v_cvt_pk_bf16_f32 v33, v28, v29
	global_store_dwordx4 v[240:241], v[30:33], off
	v_pk_mul_f32 v[14:15], v[198:199], v[14:15] op_sel_hi:[0,1]
	v_pk_mul_f32 v[16:17], v[198:199], v[16:17] op_sel_hi:[0,1]
	v_pk_mul_f32 v[10:11], v[198:199], v[10:11] op_sel_hi:[0,1]
	v_pk_mul_f32 v[12:13], v[198:199], v[12:13] op_sel_hi:[0,1]
	v_pk_mul_f32 v[6:7], v[198:199], v[6:7] op_sel_hi:[0,1]
	v_pk_mul_f32 v[8:9], v[198:199], v[8:9] op_sel_hi:[0,1]
	v_pk_mul_f32 v[2:3], v[198:199], v[2:3] op_sel_hi:[0,1]
	v_pk_mul_f32 v[4:5], v[198:199], v[4:5] op_sel_hi:[0,1]
	v_pk_mul_f32 v[200:201], v[14:15], s[40:41] op_sel_hi:[1,0]
	v_pk_mul_f32 v[202:203], v[16:17], s[40:41] op_sel_hi:[1,0]
	v_pk_mul_f32 v[204:205], v[10:11], s[40:41] op_sel_hi:[1,0]
	v_pk_mul_f32 v[206:207], v[12:13], s[40:41] op_sel_hi:[1,0]
	v_exp_f32_e32 v200, v200
	v_exp_f32_e32 v201, v201
	v_exp_f32_e32 v202, v202
	v_exp_f32_e32 v203, v203
	v_exp_f32_e32 v204, v204
	v_exp_f32_e32 v205, v205
	v_exp_f32_e32 v206, v206
	v_exp_f32_e32 v207, v207
	v_pk_add_f32 v[200:201], v[200:201], s[6:7] op_sel_hi:[1,0]
	v_pk_add_f32 v[202:203], v[202:203], s[6:7] op_sel_hi:[1,0]
	v_pk_add_f32 v[204:205], v[204:205], s[6:7] op_sel_hi:[1,0]
	v_pk_add_f32 v[206:207], v[206:207], s[6:7] op_sel_hi:[1,0]
	v_rcp_f32_e32 v200, v200
	v_rcp_f32_e32 v201, v201
	v_rcp_f32_e32 v202, v202
	v_rcp_f32_e32 v203, v203
	v_rcp_f32_e32 v204, v204
	v_rcp_f32_e32 v205, v205
	v_rcp_f32_e32 v206, v206
	v_rcp_f32_e32 v207, v207
	v_pk_mul_f32 v[14:15], v[14:15], v[200:201]
	v_pk_mul_f32 v[16:17], v[16:17], v[202:203]
	v_pk_mul_f32 v[10:11], v[10:11], v[204:205]
	v_pk_mul_f32 v[12:13], v[12:13], v[206:207]
	v_pk_mul_f32 v[14:15], v[14:15], v[6:7]
	v_pk_mul_f32 v[16:17], v[16:17], v[8:9]
	v_pk_mul_f32 v[10:11], v[10:11], v[2:3]
	v_pk_mul_f32 v[12:13], v[12:13], v[4:5]
	v_cvt_pk_bf16_f32 v14, v14, v15
	v_cvt_pk_bf16_f32 v15, v16, v17
	v_cvt_pk_bf16_f32 v16, v10, v11
	v_cvt_pk_bf16_f32 v17, v12, v13
	global_store_dwordx4 v[242:243], v[14:17], off
	s_mov_b64 s[2:3], -1
	s_andn2_b64 vcc, exec, s[38:39]
	s_cbranch_vccnz .LBB0_557
	s_nop 0
	v_lshl_add_u32 v2, s36, 8, v144
	v_ashrrev_i32_e32 v3, 31, v2
	v_lshl_add_u64 v[2:3], v[2:3], 3, s[4:5]
	flat_load_dwordx2 v[158:159], v[2:3]
	flat_load_dwordx2 v[156:157], v[2:3] offset:128
	flat_load_dwordx2 v[154:155], v[2:3] offset:256
	flat_load_dwordx2 v[152:153], v[2:3] offset:384
	flat_load_dwordx2 v[150:151], v[2:3] offset:1024
	flat_load_dwordx2 v[148:149], v[2:3] offset:1152
	flat_load_dwordx2 v[142:143], v[2:3] offset:1280
	flat_load_dwordx2 v[140:141], v[2:3] offset:1408
	s_andn2_b64 vcc, exec, s[28:29]
	s_cbranch_vccnz .LBB0_556
	s_barrier
	s_branch .LBB0_556
